# prompt-attention unit prologue: the six now-dead g_k_nope gain loads removed (one exposed load round trip per unit)
# speedup vs baseline: 1.0074x; 1.0007x over previous
.LBB0_855:
	s_or_b64 exec, exec, s[0:1]
	s_ashr_i32 s0, s12, 31
	s_lshr_b32 s0, s0, 25
	v_mov_b32_e32 v59, v0
	s_add_i32 s0, s12, s0
	s_ashr_i32 s8, s0, 7
	v_readfirstlane_b32 s1, v59
	s_and_b32 s0, s0, 0xffffff80
	s_sub_i32 s4, s12, s0
	s_ashr_i32 s1, s1, 1
	v_add_u32_e32 v2, 0x200, v59
	s_ashr_i32 s0, s4, 3
	s_and_b32 s9, s4, 7
	s_lshl_b32 s4, s8, 8
	s_andn2_b32 s1, s1, 31
	v_ashrrev_i32_e32 v168, 4, v2
	v_add_u32_e32 v2, 0x400, v59
	s_sub_i32 s24, s1, s4
	v_ashrrev_i32_e32 v170, 4, v2
	v_add_u32_e32 v2, 0x600, v59
	v_and_b32_e32 v55, 31, v59
	s_addk_i32 s24, 0x700
	s_ashr_i32 s1, s0, 31
	v_ashrrev_i32_e32 v166, 4, v59
	v_ashrrev_i32_e32 v172, 4, v2
	v_or_b32_e32 v164, s24, v55
	s_lshl_b64 s[18:19], s[0:1], 11
	v_ashrrev_i32_e32 v167, 31, v166
	v_readlane_b32 s36, v254, 28
	v_ashrrev_i32_e32 v169, 31, v168
	v_ashrrev_i32_e32 v171, 31, v170
	v_ashrrev_i32_e32 v173, 31, v172
	v_ashrrev_i32_e32 v165, 31, v164
	v_lshl_add_u64 v[4:5], s[18:19], 0, v[166:167]
	v_readlane_b32 s46, v254, 38
	v_readlane_b32 s47, v254, 39
	v_lshl_add_u64 v[6:7], s[18:19], 0, v[168:169]
	v_lshl_add_u64 v[8:9], s[18:19], 0, v[170:171]
	v_lshl_add_u64 v[10:11], s[18:19], 0, v[172:173]
	v_lshl_add_u64 v[162:163], s[18:19], 0, v[164:165]
	v_lshlrev_b64 v[4:5], 11, v[4:5]
	v_readlane_b32 s48, v254, 40
	v_readlane_b32 s49, v254, 41
	v_lshlrev_b64 v[6:7], 11, v[6:7]
	v_lshlrev_b64 v[8:9], 11, v[8:9]
	v_lshlrev_b64 v[10:11], 11, v[10:11]
	v_mov_b64_e32 v[12:13], s[46:47]
	v_lshl_add_u64 v[4:5], s[48:49], 0, v[4:5]
	s_lshl_b32 s12, s9, 8
	v_lshl_add_u64 v[6:7], s[48:49], 0, v[6:7]
	v_lshl_add_u64 v[8:9], s[48:49], 0, v[8:9]
	v_lshl_add_u64 v[10:11], s[48:49], 0, v[10:11]
	v_mad_u64_u32 v[12:13], s[0:1], v162, s3, v[12:13]
	v_bfe_u32 v51, v59, 5, 1
	v_lshl_add_u64 v[4:5], v[4:5], 0, s[12:13]
	v_lshl_add_u64 v[6:7], v[6:7], 0, s[12:13]
	v_lshl_add_u64 v[8:9], v[8:9], 0, s[12:13]
	v_lshl_add_u64 v[10:11], v[10:11], 0, s[12:13]
	v_mad_i32_i24 v13, v163, s3, v13
	s_mul_i32 s12, s9, 0xc0
	v_lshl_add_u64 v[12:13], v[12:13], 0, s[12:13]
	v_lshlrev_b32_e32 v62, 4, v51
	v_mov_b32_e32 v63, v3
	v_lshl_add_u64 v[12:13], v[12:13], 0, v[62:63]
	global_load_dwordx4 v[74:77], v[12:13], off offset:96
	global_load_dwordx4 v[82:85], v[12:13], off offset:64
	global_load_dwordx4 v[88:91], v[12:13], off offset:32
	global_load_dwordx4 v[92:95], v[12:13], off
	v_lshlrev_b32_e32 v14, 3, v59
	v_and_b32_e32 v2, 0x78, v14
	v_lshlrev_b32_e32 v2, 1, v2
	v_lshl_add_u64 v[4:5], v[4:5], 0, v[2:3]
	v_ashrrev_i32_e32 v174, 2, v59
	v_lshl_add_u64 v[6:7], v[6:7], 0, v[2:3]
	global_load_dwordx4 v[116:119], v[4:5], off
	global_load_dwordx4 v[120:123], v[6:7], off
	v_lshl_add_u64 v[4:5], v[8:9], 0, v[2:3]
	v_ashrrev_i32_e32 v175, 31, v174
	v_lshl_add_u64 v[6:7], v[10:11], 0, v[2:3]
	global_load_dwordx4 v[124:127], v[4:5], off
	global_load_dwordx4 v[128:131], v[6:7], off
	v_lshl_add_u64 v[4:5], s[18:19], 0, v[174:175]
	v_readlane_b32 s40, v254, 32
	v_readlane_b32 s41, v254, 33
	v_lshlrev_b64 v[4:5], 6, v[4:5]
	v_and_b32_e32 v6, 24, v14
	v_lshl_add_u64 v[4:5], s[40:41], 0, v[4:5]
	v_lshlrev_b32_e32 v60, 1, v6
	v_mov_b32_e32 v61, v3
	v_lshl_add_u64 v[4:5], v[4:5], 0, v[60:61]
	global_load_dwordx4 v[132:135], v[4:5], off
	global_load_dwordx4 v[36:39], v[12:13], off offset:128
	global_load_dwordx4 v[40:43], v[12:13], off offset:160
	v_readlane_b32 s37, v254, 29
	v_readlane_b32 s38, v254, 30
	v_readlane_b32 s39, v254, 31
	v_readlane_b32 s42, v254, 34
	v_readlane_b32 s43, v254, 35
	v_readlane_b32 s44, v254, 36
	v_readlane_b32 s45, v254, 37
	v_readlane_b32 s50, v254, 42
	v_readlane_b32 s51, v254, 43
	v_cmp_lt_i32_e32 vcc, v200, v242
	v_readlane_b32 s36, v253, 60
	v_and_b32_e32 v61, 32, v59
	v_cndmask_b32_e32 v4, v1, v200, vcc
	v_readlane_b32 s50, v254, 10
	v_readlane_b32 s51, v254, 11
	v_lshlrev_b32_e32 v165, 2, v4
	s_nop 3
	global_load_dwordx4 v[28:31], v61, s[50:51] offset:16
	global_load_dwordx4 v[32:35], v61, s[50:51]
	global_load_dwordx4 v[20:23], v61, s[50:51] offset:80
	global_load_dwordx4 v[24:27], v61, s[50:51] offset:64
	global_load_dwordx4 v[12:15], v61, s[50:51] offset:144
	global_load_dwordx4 v[16:19], v61, s[50:51] offset:128
	global_load_dwordx4 v[4:7], v61, s[50:51] offset:208
	global_load_dwordx4 v[8:11], v61, s[50:51] offset:192
	v_lshlrev_b32_e32 v47, 5, v164
	v_readlane_b32 s37, v253, 61
	v_readlane_b32 s38, v253, 62
	v_readlane_b32 s39, v253, 63
	v_readlane_b32 s40, v254, 0
	v_readlane_b32 s41, v254, 1
	v_readlane_b32 s42, v254, 2
	v_readlane_b32 s43, v254, 3
	v_readlane_b32 s44, v254, 4
	v_readlane_b32 s45, v254, 5
	v_readlane_b32 s46, v254, 6
	v_readlane_b32 s47, v254, 7
	v_readlane_b32 s48, v254, 8
	v_readlane_b32 s49, v254, 9
	v_or_b32_e32 v48, v47, v62
	v_readlane_b32 s36, v253, 3
	v_ashrrev_i32_e32 v49, 31, v48
	v_readlane_b32 s40, v253, 7
	v_readlane_b32 s41, v253, 8
	v_readlane_b32 s44, v253, 11
	v_readlane_b32 s45, v253, 12
	v_readlane_b32 s46, v253, 13
	v_readlane_b32 s47, v253, 14
	v_readlane_b32 s48, v253, 15
	v_readlane_b32 s49, v253, 16
	v_readlane_b32 s50, v253, 17
	v_readlane_b32 s51, v253, 18
	v_lshl_add_u64 v[44:45], v[48:49], 2, s[40:41]
	v_ashrrev_i32_e32 v49, 31, v47
	v_readlane_b32 s44, v253, 40
	v_readlane_b32 s37, v253, 4
	v_readlane_b32 s38, v253, 5
	v_readlane_b32 s39, v253, 6
	global_load_dwordx3 v[44:46], v[44:45], off
	v_lshl_add_u64 v[148:149], v[48:49], 2, s[40:41]
	v_readlane_b32 s45, v253, 41
	v_readlane_b32 s46, v253, 42
	v_readlane_b32 s47, v253, 43
	s_waitcnt vmcnt(19)
	v_and_b32_e32 v65, 0xffff0000, v77
	v_lshlrev_b32_e32 v64, 16, v77
	s_waitcnt vmcnt(17)
	v_and_b32_e32 v111, 0xffff0000, v91
	s_waitcnt vmcnt(16)
	v_and_b32_e32 v145, 0xffff0000, v92
	v_lshlrev_b32_e32 v144, 16, v92
	v_mul_f32_e32 v50, v145, v145
	v_and_b32_e32 v143, 0xffff0000, v93
	v_lshlrev_b32_e32 v142, 16, v93
	v_pk_fma_f32 v[92:93], v[144:145], v[144:145], v[50:51] op_sel_hi:[1,1,0]
	v_mul_f32_e32 v50, v143, v143
	v_pk_fma_f32 v[92:93], v[142:143], v[142:143], v[92:93]
	v_and_b32_e32 v141, 0xffff0000, v94
	v_lshlrev_b32_e32 v140, 16, v94
	v_pk_add_f32 v[92:93], v[50:51], v[92:93] op_sel_hi:[0,1]
	v_lshlrev_b32_e32 v138, 16, v95
	v_pk_fma_f32 v[92:93], v[140:141], v[140:141], v[92:93]
	v_mul_f32_e32 v50, v141, v141
	v_lshlrev_b32_e32 v110, 16, v91
	v_and_b32_e32 v113, 0xffff0000, v90
	v_lshlrev_b32_e32 v112, 16, v90
	v_and_b32_e32 v139, 0xffff0000, v95
	v_mov_b32_e32 v90, v138
	v_mov_b32_e32 v91, v141
	v_pk_add_f32 v[92:93], v[50:51], v[92:93] op_sel_hi:[0,1]
	v_lshlrev_b32_e32 v136, 16, v88
	v_pk_fma_f32 v[90:91], v[90:91], v[90:91], v[92:93]
	v_mul_f32_e32 v50, v139, v139
	v_and_b32_e32 v115, 0xffff0000, v89
	v_lshlrev_b32_e32 v114, 16, v89
	v_and_b32_e32 v137, 0xffff0000, v88
	v_mov_b32_e32 v88, v136
	v_mov_b32_e32 v89, v139
	v_pk_add_f32 v[90:91], v[50:51], v[90:91] op_sel_hi:[0,1]
	v_pk_fma_f32 v[88:89], v[88:89], v[88:89], v[90:91]
	v_mul_f32_e32 v50, v137, v137
	v_and_b32_e32 v67, 0xffff0000, v76
	v_lshlrev_b32_e32 v66, 16, v76
	v_and_b32_e32 v77, 0xffff0000, v85
	v_lshlrev_b32_e32 v76, 16, v85
	v_and_b32_e32 v79, 0xffff0000, v84
	v_lshlrev_b32_e32 v78, 16, v84
	v_mov_b32_e32 v84, v114
	v_mov_b32_e32 v85, v137
	v_pk_add_f32 v[88:89], v[50:51], v[88:89] op_sel_hi:[0,1]
	v_pk_fma_f32 v[84:85], v[84:85], v[84:85], v[88:89]
	v_mul_f32_e32 v50, v115, v115
	v_and_b32_e32 v81, 0xffff0000, v83
	v_lshlrev_b32_e32 v80, 16, v83
	v_and_b32_e32 v87, 0xffff0000, v82
	v_lshlrev_b32_e32 v86, 16, v82
	v_mov_b32_e32 v82, v112
	v_mov_b32_e32 v83, v115
	v_pk_add_f32 v[84:85], v[50:51], v[84:85] op_sel_hi:[0,1]
	v_pk_fma_f32 v[82:83], v[82:83], v[82:83], v[84:85]
	v_mul_f32_e32 v50, v113, v113
	v_mov_b32_e32 v56, v110
	v_mov_b32_e32 v57, v113
	v_pk_add_f32 v[82:83], v[50:51], v[82:83] op_sel_hi:[0,1]
	v_pk_fma_f32 v[56:57], v[56:57], v[56:57], v[82:83]
	v_mul_f32_e32 v50, v111, v111
	v_mov_b32_e32 v52, v86
	v_mov_b32_e32 v53, v111
	v_pk_add_f32 v[56:57], v[50:51], v[56:57] op_sel_hi:[0,1]
	v_pk_fma_f32 v[146:147], v[52:53], v[52:53], v[56:57]
	v_or_b32_e32 v52, 4, v48
	v_ashrrev_i32_e32 v53, 31, v52
	v_lshl_add_u64 v[52:53], v[52:53], 2, s[40:41]
	global_load_dwordx3 v[56:58], v[52:53], off
	v_or_b32_e32 v52, 8, v48
	v_or_b32_e32 v48, 12, v48
	s_waitcnt vmcnt(10)
	v_and_b32_e32 v85, 0xffff0000, v43
	v_lshlrev_b32_e32 v84, 16, v39
	v_and_b32_e32 v83, 0xffff0000, v39
	v_lshlrev_b32_e32 v82, 16, v43
	v_ashrrev_i32_e32 v53, 31, v52
	v_ashrrev_i32_e32 v49, 31, v48
	v_pk_mov_b32 v[88:89], v[82:83], v[84:85] op_sel:[1,0]
	s_mov_b64 s[36:37], s[44:45]
	v_lshl_add_u64 v[52:53], v[52:53], 2, s[40:41]
	v_lshl_add_u64 v[48:49], v[48:49], 2, s[40:41]
	v_pk_mul_f32 v[156:157], v[88:89], v[88:89]
	v_pk_mov_b32 v[88:89], v[84:85], v[82:83] op_sel:[1,0]
	s_mov_b64 s[38:39], s[46:47]
	global_load_dwordx3 v[52:54], v[52:53], off
	s_nop 0
	global_load_dword v151, v[148:149], off offset:12
	global_load_dword v153, v[148:149], off offset:28
	global_load_dword v47, v[148:149], off offset:44
	v_pk_mul_f32 v[158:159], v[88:89], v[88:89]
	global_load_dwordx3 v[48:50], v[48:49], off
	s_nop 0
	global_load_dwordx4 v[88:91], v61, s[38:39] offset:16
	global_load_dwordx4 v[92:95], v61, s[38:39]
	global_load_dwordx4 v[96:99], v61, s[38:39] offset:80
	global_load_dwordx4 v[100:103], v61, s[38:39] offset:64
	v_lshlrev_b32_e32 v186, 16, v40
	v_and_b32_e32 v187, 0xffff0000, v36
	v_lshlrev_b32_e32 v178, 16, v37
	v_and_b32_e32 v181, 0xffff0000, v37
	v_lshlrev_b32_e32 v184, 16, v36
	v_pk_mul_f32 v[36:37], v[186:187], v[186:187]
	v_mov_b32_e32 v202, v184
	v_mov_b32_e32 v203, v87
	v_pk_mov_b32 v[36:37], v[36:37], v[146:147] op_sel:[1,0]
	v_mov_b32_e32 v196, v178
	v_mov_b32_e32 v197, v80
	v_pk_fma_f32 v[36:37], v[202:203], v[202:203], v[36:37]
	v_lshlrev_b32_e32 v176, 16, v38
	v_mov_b32_e32 v198, v181
	v_mov_b32_e32 v199, v81
	v_pk_fma_f32 v[36:37], v[196:197], v[196:197], v[36:37]
	v_and_b32_e32 v43, 0xffff0000, v38
	v_mov_b32_e32 v188, v176
	v_mov_b32_e32 v189, v78
	v_pk_fma_f32 v[36:37], v[198:199], v[198:199], v[36:37]
	v_pk_mul_f32 v[108:109], v[76:77], v[76:77]
	v_and_b32_e32 v185, 0xffff0000, v40
	v_mov_b32_e32 v190, v43
	v_mov_b32_e32 v191, v79
	v_pk_fma_f32 v[36:37], v[188:189], v[188:189], v[36:37]
	v_and_b32_e32 v69, 0xffff0000, v75
	v_lshlrev_b32_e32 v68, 16, v75
	v_and_b32_e32 v75, 0xffff0000, v74
	v_lshlrev_b32_e32 v74, 16, v74
	v_and_b32_e32 v179, 0xffff0000, v41
	v_lshlrev_b32_e32 v180, 16, v41
	v_pk_mov_b32 v[40:41], v[184:185], v[186:187] op_sel:[1,0]
	v_pk_fma_f32 v[36:37], v[190:191], v[190:191], v[36:37]
	v_pk_mov_b32 v[146:147], v[156:157], v[108:109] op_sel:[1,0]
	v_pk_mul_f32 v[106:107], v[74:75], v[74:75]
	v_pk_mul_f32 v[40:41], v[40:41], v[40:41]
	v_pk_add_f32 v[36:37], v[146:147], v[36:37]
	v_mov_b32_e32 v157, v109
	v_pk_mov_b32 v[182:183], v[178:179], v[180:181] op_sel:[1,0]
	v_pk_add_f32 v[36:37], v[156:157], v[36:37]
	v_pk_mov_b32 v[108:109], v[40:41], v[106:107] op_sel:[1,0]
	v_pk_mul_f32 v[104:105], v[68:69], v[68:69]
	v_and_b32_e32 v177, 0xffff0000, v42
	v_lshlrev_b32_e32 v42, 16, v42
	v_pk_mul_f32 v[182:183], v[182:183], v[182:183]
	v_pk_add_f32 v[36:37], v[108:109], v[36:37]
	v_mov_b32_e32 v41, v107
	v_pk_mov_b32 v[38:39], v[176:177], v[42:43] op_sel:[1,0]
	v_pk_add_f32 v[36:37], v[40:41], v[36:37]
	v_pk_mov_b32 v[40:41], v[182:183], v[104:105] op_sel:[1,0]
	v_pk_mul_f32 v[72:73], v[66:67], v[66:67]
	v_pk_mul_f32 v[38:39], v[38:39], v[38:39]
	v_pk_add_f32 v[36:37], v[40:41], v[36:37]
	v_mov_b32_e32 v183, v105
	v_pk_add_f32 v[36:37], v[182:183], v[36:37]
	v_pk_mov_b32 v[40:41], v[38:39], v[72:73] op_sel:[1,0]
	v_pk_mul_f32 v[70:71], v[64:65], v[64:65]
	v_pk_add_f32 v[36:37], v[40:41], v[36:37]
	v_mov_b32_e32 v39, v73
	v_pk_add_f32 v[36:37], v[38:39], v[36:37]
	v_pk_mov_b32 v[38:39], v[158:159], v[70:71] op_sel:[1,0]
	v_mov_b32_e32 v159, v71
	v_pk_add_f32 v[36:37], v[38:39], v[36:37]
	global_load_dword v71, v[148:149], off offset:60
	v_pk_add_f32 v[36:37], v[158:159], v[36:37]
	ds_bpermute_b32 v39, v165, v37
	ds_bpermute_b32 v38, v165, v36
	s_waitcnt vmcnt(11)
	v_mov_b32_e32 v154, v45
	v_mov_b32_e32 v150, v45
	v_mov_b32_e32 v155, v46
	s_waitcnt vmcnt(10)
	v_mov_b32_e32 v72, v57
	s_waitcnt lgkmcnt(0)
	v_pk_add_f32 v[36:37], v[36:37], v[38:39]
	v_mov_b32_e32 v152, v57
	v_pk_fma_f32 v[40:41], v[36:37], s[14:15], v[160:161] op_sel_hi:[1,1,0]
	s_waitcnt vmcnt(8)
	v_mov_b32_e32 v45, v151
	v_mul_f32_e32 v36, 0x4b800000, v41
	v_cmp_gt_f32_e32 vcc, s10, v41
	s_waitcnt vmcnt(7)
	v_mov_b32_e32 v57, v153
	v_mov_b32_e32 v73, v58
	v_cndmask_b32_e32 v36, v41, v36, vcc
	v_rsq_f32_e32 v36, v36
	v_mov_b32_e32 v104, v53
	v_mov_b32_e32 v105, v54
	v_readlane_b32 s42, v253, 9
	v_mul_f32_e32 v37, 0x45800000, v36
	v_cndmask_b32_e32 v36, v36, v37, vcc
	v_mul_f32_e32 v38, 0x3e16c740, v36
	v_pk_mul_f32 v[36:37], v[38:39], v[144:145] op_sel_hi:[0,1]
	v_pk_mul_f32 v[32:33], v[32:33], v[36:37]
	v_pk_mul_f32 v[36:37], v[38:39], v[142:143] op_sel_hi:[0,1]
	v_pk_mul_f32 v[34:35], v[34:35], v[36:37]
	v_pk_mul_f32 v[36:37], v[38:39], v[140:141] op_sel_hi:[0,1]
	v_pk_mul_f32 v[36:37], v[28:29], v[36:37]
	v_pk_mul_f32 v[28:29], v[38:39], v[138:139] op_sel_hi:[0,1]
	v_pk_mul_f32 v[108:109], v[30:31], v[28:29]
	v_cvt_pk_bf16_f32 v28, v32, v33
	v_pk_mul_f32 v[32:33], v[38:39], v[136:137] op_sel_hi:[0,1]
	v_pk_mul_f32 v[24:25], v[24:25], v[32:33]
	v_pk_mul_f32 v[32:33], v[38:39], v[114:115] op_sel_hi:[0,1]
	v_pk_mul_f32 v[32:33], v[26:27], v[32:33]
	v_pk_mul_f32 v[26:27], v[38:39], v[112:113] op_sel_hi:[0,1]
	v_pk_mul_f32 v[20:21], v[20:21], v[26:27]
	v_cvt_pk_bf16_f32 v30, v34, v35
	v_cvt_pk_bf16_f32 v34, v20, v21
	v_pk_mul_f32 v[20:21], v[38:39], v[86:87] op_sel_hi:[0,1]
	v_pk_mul_f32 v[16:17], v[16:17], v[20:21]
	v_pk_mul_f32 v[20:21], v[38:39], v[80:81] op_sel_hi:[0,1]
	v_pk_mul_f32 v[18:19], v[18:19], v[20:21]
	v_pk_mul_f32 v[20:21], v[38:39], v[78:79] op_sel_hi:[0,1]
	v_pk_mul_f32 v[20:21], v[12:13], v[20:21]
	v_pk_mul_f32 v[12:13], v[38:39], v[76:77] op_sel_hi:[0,1]
	v_pk_mul_f32 v[14:15], v[14:15], v[12:13]
	v_pk_mul_f32 v[26:27], v[38:39], v[110:111] op_sel_hi:[0,1]
	v_cvt_pk_bf16_f32 v35, v14, v15
	v_pk_mul_f32 v[14:15], v[38:39], v[74:75] op_sel_hi:[0,1]
	v_pk_mul_f32 v[8:9], v[8:9], v[14:15]
	v_pk_mul_f32 v[14:15], v[38:39], v[68:69] op_sel_hi:[0,1]
	v_pk_mul_f32 v[10:11], v[10:11], v[14:15]
	v_pk_mul_f32 v[14:15], v[38:39], v[66:67] op_sel_hi:[0,1]
	v_pk_mul_f32 v[4:5], v[4:5], v[14:15]
	v_pk_mul_f32 v[14:15], v[38:39], v[64:65] op_sel_hi:[0,1]
	v_cvt_pk_bf16_f32 v38, v8, v9
	v_mul_f32_e32 v8, 0x4b800000, v40
	v_cmp_gt_f32_e32 vcc, s10, v40
	v_cvt_pk_bf16_f32 v41, v4, v5
	v_pk_mul_f32 v[6:7], v[6:7], v[14:15]
	v_cndmask_b32_e32 v8, v40, v8, vcc
	v_rsq_f32_e32 v8, v8
	v_cvt_pk_bf16_f32 v39, v6, v7
	s_waitcnt vmcnt(1)
	v_mov_b32_e32 v9, v101
	v_mov_b32_e32 v101, v93
	v_mul_f32_e32 v4, 0x45800000, v8
	v_cndmask_b32_e32 v4, v8, v4, vcc
	v_mul_f32_e32 v4, 0x3e16c740, v4
	v_pk_mul_f32 v[6:7], v[4:5], v[184:185] op_sel_hi:[0,1]
	v_mov_b32_e32 v8, v92
	v_pk_mul_f32 v[6:7], v[8:9], v[6:7]
	v_pk_mul_f32 v[8:9], v[4:5], v[186:187] op_sel_hi:[0,1]
	v_pk_mul_f32 v[8:9], v[100:101], v[8:9]
	v_cvt_pk_bf16_f32 v13, v16, v17
	v_mov_b32_e32 v16, v8
	v_mov_b32_e32 v17, v7
	v_cvt_pk_bf16_f32 v40, v10, v11
	v_mov_b32_e32 v10, v44
	v_mov_b32_e32 v11, v46
	v_mov_b32_e32 v14, v6
	v_mov_b32_e32 v15, v9
	v_pk_mul_f32 v[16:17], v[150:151], v[16:17]
	v_pk_mul_f32 v[8:9], v[44:45], v[8:9]
	v_pk_fma_f32 v[10:11], v[10:11], v[14:15], v[16:17] neg_lo:[0,0,1] neg_hi:[0,0,1]
	v_pk_fma_f32 v[6:7], v[154:155], v[6:7], v[8:9]
	v_pk_mul_f32 v[8:9], v[4:5], v[178:179] op_sel_hi:[0,1]
	v_mov_b32_e32 v14, v94
	v_mov_b32_e32 v15, v103
	v_pk_mul_f32 v[8:9], v[14:15], v[8:9]
	v_pk_mul_f32 v[14:15], v[4:5], v[180:181] op_sel_hi:[0,1]
	v_mov_b32_e32 v103, v95
	v_pk_mul_f32 v[14:15], v[102:103], v[14:15]
	v_cvt_pk_bf16_f32 v31, v36, v37
	v_cvt_pk_bf16_f32 v37, v20, v21
	v_mov_b32_e32 v20, v14
	v_mov_b32_e32 v21, v9
	v_cvt_pk_bf16_f32 v36, v18, v19
	v_mov_b32_e32 v16, v56
	v_mov_b32_e32 v17, v58
	v_mov_b32_e32 v18, v8
	v_mov_b32_e32 v19, v15
	v_pk_mul_f32 v[20:21], v[152:153], v[20:21]
	v_pk_mul_f32 v[14:15], v[56:57], v[14:15]
	v_pk_fma_f32 v[16:17], v[16:17], v[18:19], v[20:21] neg_lo:[0,0,1] neg_hi:[0,0,1]
	v_pk_fma_f32 v[8:9], v[72:73], v[8:9], v[14:15]
	v_pk_mul_f32 v[14:15], v[4:5], v[176:177] op_sel_hi:[0,1]
	v_mov_b32_e32 v18, v88
	v_mov_b32_e32 v19, v97
	v_pk_mul_f32 v[14:15], v[14:15], v[18:19]
	v_pk_mul_f32 v[18:19], v[4:5], v[42:43] op_sel_hi:[0,1]
	v_mov_b32_e32 v97, v89
	v_pk_mul_f32 v[18:19], v[18:19], v[96:97]
	v_mov_b32_e32 v46, v53
	v_mov_b32_e32 v53, v47
	v_pk_mul_f32 v[22:23], v[22:23], v[26:27]
	v_cvt_pk_bf16_f32 v27, v24, v25
	v_mov_b32_e32 v21, v19
	v_mov_b32_e32 v24, v18
	v_pk_mul_f32 v[18:19], v[18:19], v[52:53]
	v_readlane_b32 s43, v253, 10
	v_mov_b32_e32 v20, v14
	v_mov_b32_e32 v25, v15
	v_pk_fma_f32 v[14:15], v[14:15], v[104:105], v[18:19]
	v_cvt_pk_bf16_f32 v33, v32, v33
	v_cvt_pk_bf16_f32 v142, v14, v15
	global_load_dwordx2 v[14:15], v3, s[42:43]
	v_cvt_pk_bf16_f32 v32, v22, v23
	v_mov_b32_e32 v22, v52
	v_mov_b32_e32 v23, v54
	v_pk_mul_f32 v[24:25], v[24:25], v[46:47]
	v_pk_mul_f32 v[18:19], v[4:5], v[84:85] op_sel_hi:[0,1]
	v_pk_fma_f32 v[20:21], v[20:21], v[22:23], v[24:25] neg_lo:[0,0,1] neg_hi:[0,0,1]
	v_mov_b32_e32 v22, v90
	v_mov_b32_e32 v23, v99
	v_pk_mul_f32 v[4:5], v[4:5], v[82:83] op_sel_hi:[0,1]
	v_mov_b32_e32 v99, v91
	v_mov_b32_e32 v106, v49
	v_pk_mul_f32 v[18:19], v[18:19], v[22:23]
	v_pk_mul_f32 v[4:5], v[4:5], v[98:99]
	v_mov_b32_e32 v70, v49
	s_waitcnt vmcnt(1)
	v_mov_b32_e32 v49, v71
	v_mov_b32_e32 v107, v50
	v_mov_b32_e32 v23, v5
	v_mov_b32_e32 v42, v4
	v_mov_b32_e32 v43, v19
	v_pk_mul_f32 v[4:5], v[4:5], v[48:49]
	v_mov_b32_e32 v22, v18
	v_mov_b32_e32 v24, v48
	v_mov_b32_e32 v25, v50
	v_pk_mul_f32 v[42:43], v[42:43], v[70:71]
	v_pk_fma_f32 v[4:5], v[18:19], v[106:107], v[4:5]
	v_pk_fma_f32 v[22:23], v[22:23], v[24:25], v[42:43] neg_lo:[0,0,1] neg_hi:[0,0,1]
	v_cvt_pk_bf16_f32 v42, v4, v5
	v_and_b32_e32 v5, 0xffff0000, v28
	v_lshlrev_b32_e32 v4, 16, v28
	v_mul_f32_e32 v44, v5, v5
	v_fmac_f32_e32 v44, v4, v4
	v_lshlrev_b32_e32 v4, 16, v30
	v_fmac_f32_e32 v44, v4, v4
	v_and_b32_e32 v4, 0xffff0000, v30
	v_fmac_f32_e32 v44, v4, v4
	v_lshlrev_b32_e32 v4, 16, v31
	v_cvt_pk_bf16_f32 v29, v108, v109
	v_fmac_f32_e32 v44, v4, v4
	v_and_b32_e32 v4, 0xffff0000, v31
	v_fmac_f32_e32 v44, v4, v4
	v_lshlrev_b32_e32 v4, 16, v29
	v_fmac_f32_e32 v44, v4, v4
	v_and_b32_e32 v4, 0xffff0000, v29
	v_fmac_f32_e32 v44, v4, v4
	v_lshlrev_b32_e32 v4, 16, v27
	v_fmac_f32_e32 v44, v4, v4
	v_and_b32_e32 v4, 0xffff0000, v27
	v_fmac_f32_e32 v44, v4, v4
	v_lshlrev_b32_e32 v4, 16, v33
	v_fmac_f32_e32 v44, v4, v4
	v_and_b32_e32 v4, 0xffff0000, v33
	v_fmac_f32_e32 v44, v4, v4
	v_lshlrev_b32_e32 v4, 16, v34
	v_fmac_f32_e32 v44, v4, v4
	v_and_b32_e32 v4, 0xffff0000, v34
	v_fmac_f32_e32 v44, v4, v4
	v_lshlrev_b32_e32 v4, 16, v32
	v_cvt_pk_bf16_f32 v136, v10, v11
	v_fmac_f32_e32 v44, v4, v4
	v_and_b32_e32 v4, 0xffff0000, v32
	v_cvt_pk_bf16_f32 v137, v16, v17
	v_fmac_f32_e32 v44, v4, v4
	v_lshlrev_b32_e32 v4, 16, v13
	v_and_b32_e32 v16, 0xffff0000, v136
	v_fmac_f32_e32 v44, v4, v4
	v_and_b32_e32 v4, 0xffff0000, v13
	v_lshlrev_b32_e32 v12, 16, v136
	v_mul_f32_e32 v46, v16, v16
	v_fmac_f32_e32 v44, v4, v4
	v_lshlrev_b32_e32 v4, 16, v36
	v_fmac_f32_e32 v46, v12, v12
	v_lshlrev_b32_e32 v12, 16, v137
	v_cvt_pk_bf16_f32 v138, v20, v21
	v_fmac_f32_e32 v44, v4, v4
	v_and_b32_e32 v4, 0xffff0000, v36
	v_fmac_f32_e32 v46, v12, v12
	v_and_b32_e32 v12, 0xffff0000, v137
	v_fmac_f32_e32 v44, v4, v4
	v_lshlrev_b32_e32 v4, 16, v37
	v_fmac_f32_e32 v46, v12, v12
	v_lshlrev_b32_e32 v12, 16, v138
	v_cvt_pk_bf16_f32 v43, v22, v23
	v_fmac_f32_e32 v44, v4, v4
	v_and_b32_e32 v4, 0xffff0000, v37
	v_fmac_f32_e32 v46, v12, v12
	v_and_b32_e32 v12, 0xffff0000, v138
	v_fmac_f32_e32 v44, v4, v4
	v_lshlrev_b32_e32 v4, 16, v35
	v_fmac_f32_e32 v46, v12, v12
	v_lshlrev_b32_e32 v12, 16, v43
	v_cvt_pk_bf16_f32 v140, v6, v7
	v_fmac_f32_e32 v44, v4, v4
	v_and_b32_e32 v4, 0xffff0000, v35
	v_fmac_f32_e32 v46, v12, v12
	v_and_b32_e32 v12, 0xffff0000, v43
	v_fmac_f32_e32 v44, v4, v4
	v_lshlrev_b32_e32 v4, 16, v38
	v_fmac_f32_e32 v46, v12, v12
	v_lshlrev_b32_e32 v12, 16, v140
	v_cvt_pk_bf16_f32 v141, v8, v9
	v_and_b32_e32 v5, 0xffff0000, v38
	v_fmac_f32_e32 v46, v12, v12
	v_and_b32_e32 v12, 0xffff0000, v140
	v_fmac_f32_e32 v44, v4, v4
	v_lshlrev_b32_e32 v6, 16, v40
	v_fmac_f32_e32 v46, v12, v12
	v_lshlrev_b32_e32 v12, 16, v141
	v_fmac_f32_e32 v44, v5, v5
	v_and_b32_e32 v7, 0xffff0000, v40
	v_fmac_f32_e32 v46, v12, v12
	v_and_b32_e32 v12, 0xffff0000, v141
	v_fmac_f32_e32 v44, v6, v6
	v_lshlrev_b32_e32 v8, 16, v41
	v_fmac_f32_e32 v46, v12, v12
	v_lshlrev_b32_e32 v12, 16, v142
	v_fmac_f32_e32 v44, v7, v7
	v_and_b32_e32 v9, 0xffff0000, v41
	v_fmac_f32_e32 v46, v12, v12
	v_and_b32_e32 v12, 0xffff0000, v142
	v_fmac_f32_e32 v44, v8, v8
	v_lshlrev_b32_e32 v10, 16, v39
	v_fmac_f32_e32 v46, v12, v12
	v_lshlrev_b32_e32 v12, 16, v42
	v_fmac_f32_e32 v44, v9, v9
	v_and_b32_e32 v11, 0xffff0000, v39
	v_fmac_f32_e32 v46, v12, v12
	v_and_b32_e32 v12, 0xffff0000, v42
	v_fmac_f32_e32 v44, v10, v10
	v_fmac_f32_e32 v46, v12, v12
	v_fmac_f32_e32 v44, v11, v11
	v_mov_b32_e32 v48, v44
	v_mov_b32_e32 v47, v46
	v_and_b32_e32 v45, 15, v59
	v_mov_b32_e32 v16, 1.0
	v_permlane32_swap_b32_e32 v44, v48
	v_permlane32_swap_b32_e32 v46, v47
	v_cmp_gt_u32_e64 s[0:1], 8, v45
	v_lshlrev_b32_e32 v12, 5, v45
	v_mov_b32_e32 v4, 1.0
	v_mov_b32_e32 v5, v16
	v_mov_b32_e32 v6, 1.0
	v_mov_b32_e32 v7, v16
	v_mov_b32_e32 v8, 1.0
	v_mov_b32_e32 v9, v16
	v_mov_b32_e32 v10, 1.0
	v_mov_b32_e32 v11, v16
	v_readlane_b32 s48, v253, 44
	v_readlane_b32 s49, v253, 45
	v_readlane_b32 s50, v253, 46
	v_readlane_b32 s51, v253, 47
	v_readlane_b32 s52, v253, 48
	v_readlane_b32 s53, v253, 49
	v_readlane_b32 s54, v253, 50
	v_readlane_b32 s55, v253, 51
	v_readlane_b32 s56, v253, 52
	v_readlane_b32 s57, v253, 53
	v_readlane_b32 s58, v253, 54
	v_readlane_b32 s59, v253, 55
	s_and_saveexec_b64 s[4:5], s[0:1]
	s_cbranch_execz .LBB0_857
	v_readlane_b32 s36, v253, 40
	v_readlane_b32 s37, v253, 41
	s_nop 4
	v_readlane_b32 s38, v253, 42
	v_readlane_b32 s39, v253, 43
	v_readlane_b32 s40, v253, 44
	v_readlane_b32 s41, v253, 45
	v_readlane_b32 s42, v253, 46
	v_readlane_b32 s43, v253, 47
	v_readlane_b32 s44, v253, 48
	v_readlane_b32 s45, v253, 49
	v_readlane_b32 s46, v253, 50
	v_readlane_b32 s47, v253, 51
	v_readlane_b32 s48, v253, 52
	v_readlane_b32 s49, v253, 53
	v_readlane_b32 s50, v253, 54
	v_readlane_b32 s51, v253, 55
.LBB0_857:
	s_or_b64 exec, exec, s[4:5]
	v_xor_b32_e32 v17, 1, v1
	v_cmp_lt_i32_e32 vcc, v17, v242
	s_nop 1
	v_cndmask_b32_e32 v17, v1, v17, vcc
	v_lshlrev_b32_e32 v196, 2, v17
	v_xor_b32_e32 v49, 2, v1
	v_cmp_lt_i32_e32 vcc, v49, v242
	s_nop 1
	v_cndmask_b32_e32 v49, v1, v49, vcc
	v_lshlrev_b32_e32 v197, 2, v49
	v_xor_b32_e32 v49, 4, v1
	v_cmp_lt_i32_e32 vcc, v49, v242
	s_nop 1
	v_cndmask_b32_e32 v49, v1, v49, vcc
	v_lshlrev_b32_e32 v198, 2, v49
	s_waitcnt vmcnt(0)
	v_lshlrev_b32_e32 v20, 2, v166
	v_and_b32_e32 v20, 12, v20
	v_bfe_u32 v21, v166, 2, 2
	v_bitop3_b32 v20, v20, v45, v21 bitop3:0x36
	v_lshlrev_b32_e32 v199, 8, v166
	v_lshlrev_b32_e32 v201, 4, v20
	v_add3_u32 v20, 0, v201, v199
	ds_write_b128 v20, v[116:119]
	v_lshlrev_b32_e32 v17, 2, v168
	v_and_b32_e32 v17, 12, v17
	v_bfe_u32 v22, v168, 2, 2
	v_bitop3_b32 v17, v17, v45, v22 bitop3:0x36
	v_lshlrev_b32_e32 v202, 8, v168
	v_lshlrev_b32_e32 v203, 4, v17
	v_add3_u32 v17, 0, v203, v202
	ds_write_b128 v17, v[120:123]
	v_lshlrev_b32_e32 v20, 2, v170
	v_and_b32_e32 v20, 12, v20
	v_bfe_u32 v21, v170, 2, 2
	v_bitop3_b32 v20, v20, v45, v21 bitop3:0x36
	v_lshlrev_b32_e32 v204, 8, v170
	v_lshlrev_b32_e32 v205, 4, v20
	v_add3_u32 v20, 0, v205, v204
	ds_write_b128 v20, v[124:127]
	s_sub_i32 s21, 0, s8
	s_lshl_b32 s12, s9, 7
	v_add_f32_e32 v44, v44, v48
	v_mul_f32_e32 v48, 0x4f800000, v44
	v_cmp_gt_f32_e32 vcc, s11, v44
	v_add_f32_e32 v46, v46, v47
	v_and_b32_e32 v25, 63, v59
	v_cndmask_b32_e32 v44, v44, v48, vcc
	v_sqrt_f32_e32 v48, v44
	v_lshlrev_b32_e32 v218, 8, v172
	s_lshl_b32 s25, s21, 1
	s_movk_i32 s4, 0x50
	v_add_u32_e32 v47, -1, v48
	v_fma_f32 v65, -v47, v48, v44
	v_cmp_ge_f32_e64 s[8:9], 0, v65
	v_add_u32_e32 v65, 1, v48
	v_readlane_b32 s36, v254, 28
	v_cndmask_b32_e64 v47, v48, v47, s[8:9]
	v_fma_f32 v48, -v65, v48, v44
	v_cmp_lt_f32_e64 s[8:9], 0, v48
	v_lshrrev_b32_e32 v61, 16, v38
	s_add_i32 s25, s25, 16
	v_cndmask_b32_e64 v47, v47, v65, s[8:9]
	v_mul_f32_e32 v48, 0x37800000, v47
	v_cndmask_b32_e32 v47, v47, v48, vcc
	v_mul_f32_e32 v48, 0x4f800000, v46
	v_cmp_gt_f32_e32 vcc, s11, v46
	v_cmp_class_f32_e64 s[8:9], v44, v192
	s_bitset1_b32 s18, 7
	v_cndmask_b32_e32 v46, v46, v48, vcc
	v_sqrt_f32_e32 v48, v46
	v_cndmask_b32_e64 v44, v47, v44, s[8:9]
	v_mul_f32_e32 v44, 0x41000000, v44
	s_or_b32 s26, s24, 31
	v_add_u32_e32 v47, -1, v48
	v_fma_f32 v65, -v47, v48, v46
	v_cmp_ge_f32_e64 s[8:9], 0, v65
	v_add_u32_e32 v65, 1, v48
	v_readlane_b32 s48, v254, 40
	v_cndmask_b32_e64 v47, v48, v47, s[8:9]
	v_fma_f32 v48, -v65, v48, v46
	v_cmp_lt_f32_e64 s[8:9], 0, v48
	v_perm_b32 v156, v61, v38, s22
	v_readlane_b32 s37, v254, 29
	v_cndmask_b32_e64 v47, v47, v65, s[8:9]
	v_mul_f32_e32 v48, 0x37800000, v47
	v_cndmask_b32_e32 v47, v47, v48, vcc
	v_cmp_class_f32_e32 vcc, v46, v192
	v_bfe_u32 v48, v59, 1, 1
	v_readlane_b32 s38, v254, 30
	v_cndmask_b32_e32 v46, v47, v46, vcc
	v_mul_f32_e32 v46, 0x40b504f3, v46
	v_mul_f32_e32 v15, v15, v46
	v_fmac_f32_e32 v15, v14, v44
	v_lshlrev_b32_e32 v14, 2, v55
	v_and_b32_e32 v14, 12, v14
	v_bfe_u32 v44, v59, 2, 2
	v_bitop3_b32 v46, v14, v51, v44 bitop3:0x36
	v_lshlrev_b32_e32 v207, 4, v46
	v_or_b32_e32 v46, 2, v51
	v_bitop3_b32 v46, v14, v46, v44 bitop3:0x36
	v_lshlrev_b32_e32 v208, 4, v46
	v_or_b32_e32 v46, 4, v51
	v_bitop3_b32 v46, v14, v46, v44 bitop3:0x36
	v_lshlrev_b32_e32 v209, 4, v46
	v_or_b32_e32 v46, 6, v51
	v_bitop3_b32 v14, v14, v46, v44 bitop3:0x36
	v_lshlrev_b32_e32 v210, 4, v14
	v_lshrrev_b32_e32 v14, 3, v25
	v_fmamk_f32 v46, v15, 0x3f828f5c, v193
	v_and_b32_e32 v15, 4, v14
	v_or_b32_e32 v47, v15, v44
	v_and_or_b32 v14, v14, 2, v48
	v_lshlrev_b32_e32 v25, 3, v25
	v_or_b32_e32 v15, 8, v15
	v_or_b32_e32 v48, 8, v14
	v_lshlrev_b32_e32 v211, 8, v47
	v_and_b32_e32 v47, 12, v59
	v_and_b32_e32 v213, 8, v25
	v_or_b32_e32 v25, v15, v44
	v_lshrrev_b32_e32 v15, 2, v15
	v_or_b32_e32 v59, v51, v47
	v_lshlrev_b32_e32 v214, 8, v25
	v_bitop3_b32 v25, v15, v48, v47 bitop3:0x36
	v_bitop3_b32 v65, v14, v59, 8 bitop3:0x36
	v_lshlrev_b32_e32 v215, 4, v25
	v_or_b32_e32 v25, 12, v14
	v_bitop3_b32 v14, v14, v59, 12 bitop3:0x36
	v_lshlrev_b32_e32 v216, 4, v14
	v_bitop3_b32 v14, v15, v25, v47 bitop3:0x36
	v_lshlrev_b32_e32 v217, 4, v14
	v_lshlrev_b32_e32 v8, 2, v172
	v_and_b32_e32 v8, 12, v8
	v_bfe_u32 v9, v172, 2, 2
	v_bitop3_b32 v8, v8, v45, v9 bitop3:0x36
	v_lshlrev_b32_e32 v219, 4, v8
	v_add3_u32 v8, 0, v219, v218
	ds_write_b128 v8, v[128:131]
	v_mul_lo_u32 v4, v174, s4
	s_lshl_b32 s4, s12, 1
	v_readlane_b32 s39, v254, 31
	v_readlane_b32 s40, v254, 32
	v_readlane_b32 s41, v254, 33
	v_readlane_b32 s42, v254, 34
	v_readlane_b32 s43, v254, 35
	v_readlane_b32 s44, v254, 36
	v_readlane_b32 s45, v254, 37
	v_readlane_b32 s46, v254, 38
	v_readlane_b32 s47, v254, 39
	v_readlane_b32 s49, v254, 41
	v_readlane_b32 s50, v254, 42
	v_readlane_b32 s51, v254, 43
	s_add_u32 s4, s48, s4
	v_mov_b32_e32 v61, v3
	v_lshrrev_b32_e32 v56, 16, v13
	v_add3_u32 v220, s80, v4, v60
	s_addc_u32 s5, s49, 0
	v_lshl_add_u64 v[178:179], s[40:41], 0, v[60:61]
	v_readlane_b32 s36, v253, 40
	v_lshrrev_b32_e32 v49, 16, v30
	v_lshrrev_b32_e32 v50, 16, v31
	v_lshrrev_b32_e32 v57, 16, v36
	v_lshrrev_b32_e32 v58, 16, v37
	v_lshrrev_b32_e32 v63, 16, v40
	v_lshrrev_b32_e32 v64, 16, v41
	ds_write_b128 v220, v[132:135]
	v_mul_u32_u24_e32 v4, 0x50, v55
	v_perm_b32 v152, v56, v13, s22
	v_mov_b32_e32 v13, v3
	v_readlane_b32 s37, v253, 41
	v_mov_b32_e32 v16, v3
	v_mov_b32_e32 v17, v3
	s_waitcnt lgkmcnt(0)
	s_barrier
	v_add3_u32 v222, s80, v4, v62
	v_xor_b32_e32 v20, 0x80000000, v46
	v_perm_b32 v146, v50, v31, s22
	v_perm_b32 v145, v49, v30, s22
	v_perm_b32 v154, v58, v37, s22
	v_perm_b32 v153, v57, v36, s22
	v_perm_b32 v158, v64, v41, s22
	v_perm_b32 v157, v63, v40, s22
	v_bfi_b32 v159, s23, v39, v39
	v_bfi_b32 v139, s23, v43, v43
	v_bfi_b32 v143, s23, v42, v42
	v_lshlrev_b32_e32 v221, 2, v51
	v_lshl_add_u64 v[176:177], s[4:5], 0, v[2:3]
	v_lshl_add_u64 v[180:181], s[36:37], 0, v[12:13]
	v_mov_b32_e32 v240, 1.0
	v_mov_b32_e32 v241, 1.0
	v_mov_b32_e32 v243, 1.0
	v_mov_b32_e32 v252, 1.0
	v_mov_b32_e32 v248, 1.0
	v_mov_b32_e32 v249, 1.0
	v_mov_b32_e32 v250, 1.0
	v_mov_b32_e32 v251, 1.0
	s_mov_b64 vcc, exec
	s_and_b64 exec, exec, s[0:1]
	s_mov_b64 exec, vcc
	v_mov_b32_e32 v2, v3
	v_mov_b32_e32 v4, v3
	v_mov_b32_e32 v5, v3
	v_mov_b32_e32 v6, v3
	v_mov_b32_e32 v7, v3
	v_mov_b32_e32 v8, v3
	v_mov_b32_e32 v9, v3
	v_mov_b32_e32 v10, v3
	v_mov_b32_e32 v11, v3
	v_mov_b32_e32 v12, v3
	v_mov_b32_e32 v14, v3
	v_mov_b32_e32 v15, v3
	v_mov_b64_e32 v[50:51], v[16:17]
	s_waitcnt lgkmcnt(2)
	v_lshrrev_b32_e32 v26, 16, v28
	v_lshrrev_b32_e32 v52, 16, v27
	v_lshrrev_b32_e32 v53, 16, v33
	v_lshrrev_b32_e32 v54, 16, v34
	v_mov_b64_e32 v[48:49], v[14:15]
	v_mov_b64_e32 v[46:47], v[12:13]
	v_mov_b64_e32 v[44:45], v[10:11]
	v_mov_b64_e32 v[42:43], v[8:9]
	v_mov_b64_e32 v[40:41], v[6:7]
	v_mov_b64_e32 v[38:39], v[4:5]
	v_mov_b64_e32 v[36:37], v[2:3]
	v_mov_b64_e32 v[18:19], v[16:17]
	s_mov_b32 s20, 0
	v_lshlrev_b32_e32 v206, 8, v55
	v_lshlrev_b32_e32 v212, 4, v65
	v_perm_b32 v144, v26, v28, s22
	v_bfi_b32 v147, s23, v29, v29
	v_perm_b32 v150, v54, v34, s22
	v_perm_b32 v149, v53, v33, s22
	v_perm_b32 v148, v52, v27, s22
	v_bfi_b32 v151, s23, v32, v32
	v_bfi_b32 v155, s23, v35, v35
	v_mov_b32_e32 v21, v20
	v_mov_b32_e32 v22, v20
	v_mov_b32_e32 v23, v20
	v_mov_b32_e32 v24, v20
	v_mov_b32_e32 v25, v20
	v_mov_b32_e32 v26, v20
	v_mov_b32_e32 v27, v20
	v_mov_b32_e32 v28, v20
	v_mov_b32_e32 v29, v20
	v_mov_b32_e32 v30, v20
	v_mov_b32_e32 v31, v20
	v_mov_b32_e32 v32, v20
	v_mov_b32_e32 v33, v20
	v_mov_b32_e32 v34, v20
	v_mov_b32_e32 v35, v20
	v_mov_b32_e32 v223, 0
	s_movk_i32 s27, 0x7f
	v_mov_b64_e32 v[16:17], v[14:15]
	v_mov_b64_e32 v[14:15], v[12:13]
	v_mov_b64_e32 v[12:13], v[10:11]
	v_mov_b64_e32 v[10:11], v[8:9]
	v_mov_b64_e32 v[8:9], v[6:7]
	v_mov_b64_e32 v[6:7], v[4:5]
	v_mov_b64_e32 v[4:5], v[2:3]
	v_readlane_b32 s38, v253, 42
	v_readlane_b32 s39, v253, 43
	v_readlane_b32 s40, v253, 44
	v_readlane_b32 s41, v253, 45
	v_readlane_b32 s42, v253, 46
	v_readlane_b32 s43, v253, 47
	v_readlane_b32 s44, v253, 48
	v_readlane_b32 s45, v253, 49
	v_readlane_b32 s46, v253, 50
	v_readlane_b32 s47, v253, 51
	v_readlane_b32 s48, v253, 52
	v_readlane_b32 s49, v253, 53
	v_readlane_b32 s50, v253, 54
	v_readlane_b32 s51, v253, 55
